# RWKV epilogue (GroupNorm + gate) with packed f32 math over the two tokens of a wave and each pair of 64-lane sums folded by one permlane swap into a single DPP chain; sigmoid work fills the chain's wa
# speedup vs baseline: 1.0095x; 1.0095x over previous
.Lrw_epi:
	v_and_b32_e32 v166, 63, v180
	v_lshrrev_b32_e32 v167, 6, v180
	v_subrev_u32_e32 v167, 4, v167
	v_add_u32_e32 v124, s72, v166
	v_lshlrev_b32_e32 v156, 2, v124
	v_lshlrev_b32_e32 v124, 1, v124
	v_lshl_add_u32 v124, v167, 10, v124
	s_add_u32 s0, s80, s17
	s_lshl_b32 s0, s0, 10
	s_add_u32 s10, s50, s0
	s_addc_u32 s11, s51, 0
	s_add_u32 s12, s24, s0
	s_addc_u32 s13, s25, 0
	global_load_ushort v128, v124, s[10:11]
	s_add_u32 s10, s10, 0x1000
	s_addc_u32 s11, s11, 0
	global_load_ushort v129, v124, s[10:11]
	s_add_u32 s10, s10, 0x1000
	s_addc_u32 s11, s11, 0
	global_load_ushort v130, v124, s[10:11]
	s_add_u32 s10, s10, 0x1000
	s_addc_u32 s11, s11, 0
	global_load_ushort v131, v124, s[10:11]
	s_add_u32 s10, s10, 0x1000
	s_addc_u32 s11, s11, 0
	global_load_ushort v132, v124, s[10:11]
	s_add_u32 s10, s10, 0x1000
	s_addc_u32 s11, s11, 0
	global_load_ushort v133, v124, s[10:11]
	s_add_u32 s10, s10, 0x1000
	s_addc_u32 s11, s11, 0
	global_load_ushort v134, v124, s[10:11]
	s_add_u32 s10, s10, 0x1000
	s_addc_u32 s11, s11, 0
	global_load_ushort v135, v124, s[10:11]
	s_add_u32 s10, s10, 0x1000
	s_addc_u32 s11, s11, 0
	global_load_ushort v136, v124, s[10:11]
	s_add_u32 s10, s10, 0x1000
	s_addc_u32 s11, s11, 0
	global_load_ushort v137, v124, s[10:11]
	s_add_u32 s10, s10, 0x1000
	s_addc_u32 s11, s11, 0
	global_load_ushort v138, v124, s[10:11]
	s_add_u32 s10, s10, 0x1000
	s_addc_u32 s11, s11, 0
	global_load_ushort v139, v124, s[10:11]
	s_add_u32 s10, s10, 0x1000
	s_addc_u32 s11, s11, 0
	global_load_ushort v140, v124, s[10:11]
	s_add_u32 s10, s10, 0x1000
	s_addc_u32 s11, s11, 0
	global_load_ushort v141, v124, s[10:11]
	s_add_u32 s10, s10, 0x1000
	s_addc_u32 s11, s11, 0
	global_load_ushort v142, v124, s[10:11]
	s_add_u32 s10, s10, 0x1000
	s_addc_u32 s11, s11, 0
	global_load_ushort v143, v124, s[10:11]
	s_add_u32 s10, s10, 0x1000
	s_addc_u32 s11, s11, 0
	global_load_dword v144, v156, s[58:59]
	global_load_dword v145, v156, s[60:61]
	v_lshl_add_u32 v146, v167, 6, v166
	v_lshlrev_b32_e32 v146, 2, v146
	v_add_u32_e32 v147, s41, v146
	v_add_u32_e32 v146, 0x1f800, v146
	v_lshlrev_b32_e32 v148, 2, v167
	v_add_u32_e32 v148, s16, v148
	v_mov_b32_e32 v125, 0xbc800000
	v_mov_b32_e32 v126, 0x3c800000
	v_mov_b32_e32 v127, 0x3a27c5ac
	v_mov_b32_e32 v149, 0x27f00
	s_lshl_b32 s15, s40, 2
	s_add_u32 s15, s15, 4
	s_mov_b32 s8, 0xbfb8aa3b

.Lrw_go_0:
	s_waitcnt vmcnt(0)
	ds_read2st64_b32 v[150:151], v146 offset0:0 offset1:4
	ds_read2st64_b32 v[152:153], v147 offset0:0 offset1:4
	ds_read2_b32 v[154:155], v148 offset0:0 offset1:4
	v_lshlrev_b32_e32 v128, 16, v128
	v_lshlrev_b32_e32 v129, 16, v129
	s_waitcnt lgkmcnt(0)
	v_pk_mov_b32 v[156:157], v[150:151], v[150:151] op_sel:[0,1]
	s_nop 1
	v_permlane32_swap_b32_e32 v156, v157
	v_add_f32_e32 v156, v156, v157
	v_pk_mul_f32 v[162:163], v[128:129], s[8:9] op_sel_hi:[1,0]
	v_exp_f32_e32 v162, v162
	v_add_f32_dpp v156, v156, v156 quad_perm:[1,0,3,2] row_mask:0xf bank_mask:0xf bound_ctrl:1
	v_exp_f32_e32 v163, v163
	s_nop 0
	v_add_f32_dpp v156, v156, v156 quad_perm:[2,3,0,1] row_mask:0xf bank_mask:0xf bound_ctrl:1
	s_nop 0
	s_nop 0
	v_add_f32_dpp v156, v156, v156 row_half_mirror row_mask:0xf bank_mask:0xf bound_ctrl:1
	s_nop 0
	s_nop 0
	v_add_f32_dpp v156, v156, v156 row_mirror row_mask:0xf bank_mask:0xf bound_ctrl:1
	s_nop 0
	s_nop 0
	v_add_f32_dpp v156, v156, v156 row_bcast:15 row_mask:0xa bank_mask:0xf
	s_nop 0
	v_readlane_b32 s4, v156, 31
	v_readlane_b32 s5, v156, 63
	s_nop 1
	v_pk_fma_f32 v[150:151], s[4:5], v[124:125], v[150:151] op_sel:[0,1,0] op_sel_hi:[1,1,1]
	v_pk_mul_f32 v[158:159], v[150:151], v[150:151]
	s_nop 1
	v_permlane32_swap_b32_e32 v158, v159
	v_add_f32_e32 v158, v158, v159
	v_pk_add_f32 v[162:163], v[162:163], 1.0 op_sel_hi:[1,0]
	v_rcp_f32_e32 v162, v162
	v_add_f32_dpp v158, v158, v158 quad_perm:[1,0,3,2] row_mask:0xf bank_mask:0xf bound_ctrl:1
	v_rcp_f32_e32 v163, v163
	s_nop 0
	v_add_f32_dpp v158, v158, v158 quad_perm:[2,3,0,1] row_mask:0xf bank_mask:0xf bound_ctrl:1
	s_nop 0
	s_nop 0
	v_add_f32_dpp v158, v158, v158 row_half_mirror row_mask:0xf bank_mask:0xf bound_ctrl:1
	s_nop 0
	s_nop 0
	v_add_f32_dpp v158, v158, v158 row_mirror row_mask:0xf bank_mask:0xf bound_ctrl:1
	s_nop 0
	s_nop 0
	v_add_f32_dpp v158, v158, v158 row_bcast:15 row_mask:0xa bank_mask:0xf
	s_nop 0
	v_readlane_b32 s6, v158, 31
	v_readlane_b32 s7, v158, 63
	s_nop 1
	v_pk_fma_f32 v[160:161], s[6:7], v[126:127], v[126:127] op_sel:[0,0,1] op_sel_hi:[1,0,1]
	v_rsq_f32_e32 v160, v160
	v_rsq_f32_e32 v161, v161
	s_nop 0
	v_pk_mul_f32 v[164:165], v[150:151], v[160:161]
	v_pk_fma_f32 v[164:165], v[144:145], v[164:165], v[144:145] op_sel:[0,0,1] op_sel_hi:[0,1,1]
	v_pk_fma_f32 v[164:165], v[154:155], v[152:153], v[164:165]
	v_pk_mul_f32 v[164:165], v[164:165], v[128:129]
	v_pk_mul_f32 v[164:165], v[162:163], v[164:165]
	v_bfe_u32 v156, v164, 16, 1
	v_add3_u32 v164, v164, v156, s97
	v_bfe_u32 v157, v165, 16, 1
	v_add3_u32 v165, v165, v157, s97
	global_store_short_d16_hi v124, v164, s[12:13]
	s_add_u32 s12, s12, 0x1000
	s_addc_u32 s13, s13, 0
	global_store_short_d16_hi v124, v165, s[12:13]
	s_add_u32 s12, s12, 0x1000
	s_addc_u32 s13, s13, 0
	s_cmp_lg_u32 s40, 31
	s_cbranch_scc0 .Lrw_nopf
	s_add_i32 s3, s17, 64
	s_add_u32 s0, s80, s3
	s_addc_u32 s1, s81, 0
	v_ashrrev_i32_e32 v27, 31, v26
	v_lshl_add_u64 v[4:5], s[0:1], 0, v[26:27]
	v_mad_u64_u32 v[2:3], s[0:1], v4, s83, 0
	v_mad_i32_i24 v3, v5, s83, v3
	v_add_u32_e32 v1, s3, v26
	v_mov_b32_e32 v95, v94
	v_lshl_add_u64 v[2:3], s[46:47], 0, v[2:3]
	v_cmp_lt_i32_e32 vcc, 0, v1
	v_mov_b32_e32 v106, 0
	v_lshl_add_u64 v[2:3], v[28:29], 1, v[2:3]
	v_mov_b64_e32 v[34:35], v[94:95]
	s_and_saveexec_b64 s[0:1], vcc
	s_cbranch_execz .Lrw_pf585
	global_load_ushort v52, v[2:3], off offset:-3072
	global_load_ushort v53, v[2:3], off offset:-2048
	global_load_ushort v54, v[2:3], off offset:-1024

.Lrw_go_1:
	ds_read2st64_b32 v[150:151], v146 offset0:8 offset1:12
	ds_read2st64_b32 v[152:153], v147 offset0:8 offset1:12
	ds_read2_b32 v[154:155], v148 offset0:8 offset1:12
	v_lshlrev_b32_e32 v130, 16, v130
	v_lshlrev_b32_e32 v131, 16, v131
	s_waitcnt lgkmcnt(0)
	v_pk_mov_b32 v[156:157], v[150:151], v[150:151] op_sel:[0,1]
	s_nop 1
	v_permlane32_swap_b32_e32 v156, v157
	v_add_f32_e32 v156, v156, v157
	v_pk_mul_f32 v[162:163], v[130:131], s[8:9] op_sel_hi:[1,0]
	v_exp_f32_e32 v162, v162
	v_add_f32_dpp v156, v156, v156 quad_perm:[1,0,3,2] row_mask:0xf bank_mask:0xf bound_ctrl:1
	v_exp_f32_e32 v163, v163
	s_nop 0
	v_add_f32_dpp v156, v156, v156 quad_perm:[2,3,0,1] row_mask:0xf bank_mask:0xf bound_ctrl:1
	s_nop 0
	s_nop 0
	v_add_f32_dpp v156, v156, v156 row_half_mirror row_mask:0xf bank_mask:0xf bound_ctrl:1
	s_nop 0
	s_nop 0
	v_add_f32_dpp v156, v156, v156 row_mirror row_mask:0xf bank_mask:0xf bound_ctrl:1
	s_nop 0
	s_nop 0
	v_add_f32_dpp v156, v156, v156 row_bcast:15 row_mask:0xa bank_mask:0xf
	s_nop 0
	v_readlane_b32 s4, v156, 31
	v_readlane_b32 s5, v156, 63
	s_nop 1
	v_pk_fma_f32 v[150:151], s[4:5], v[124:125], v[150:151] op_sel:[0,1,0] op_sel_hi:[1,1,1]
	v_pk_mul_f32 v[158:159], v[150:151], v[150:151]
	s_nop 1
	v_permlane32_swap_b32_e32 v158, v159
	v_add_f32_e32 v158, v158, v159
	v_pk_add_f32 v[162:163], v[162:163], 1.0 op_sel_hi:[1,0]
	v_rcp_f32_e32 v162, v162
	v_add_f32_dpp v158, v158, v158 quad_perm:[1,0,3,2] row_mask:0xf bank_mask:0xf bound_ctrl:1
	v_rcp_f32_e32 v163, v163
	s_nop 0
	v_add_f32_dpp v158, v158, v158 quad_perm:[2,3,0,1] row_mask:0xf bank_mask:0xf bound_ctrl:1
	s_nop 0
	s_nop 0
	v_add_f32_dpp v158, v158, v158 row_half_mirror row_mask:0xf bank_mask:0xf bound_ctrl:1
	s_nop 0
	s_nop 0
	v_add_f32_dpp v158, v158, v158 row_mirror row_mask:0xf bank_mask:0xf bound_ctrl:1
	s_nop 0
	s_nop 0
	v_add_f32_dpp v158, v158, v158 row_bcast:15 row_mask:0xa bank_mask:0xf
	s_nop 0
	v_readlane_b32 s6, v158, 31
	v_readlane_b32 s7, v158, 63
	s_nop 1
	v_pk_fma_f32 v[160:161], s[6:7], v[126:127], v[126:127] op_sel:[0,0,1] op_sel_hi:[1,0,1]
	v_rsq_f32_e32 v160, v160
	v_rsq_f32_e32 v161, v161
	s_nop 0
	v_pk_mul_f32 v[164:165], v[150:151], v[160:161]
	v_pk_fma_f32 v[164:165], v[144:145], v[164:165], v[144:145] op_sel:[0,0,1] op_sel_hi:[0,1,1]
	v_pk_fma_f32 v[164:165], v[154:155], v[152:153], v[164:165]
	v_pk_mul_f32 v[164:165], v[164:165], v[130:131]
	v_pk_mul_f32 v[164:165], v[162:163], v[164:165]
	v_bfe_u32 v156, v164, 16, 1
	v_add3_u32 v164, v164, v156, s97
	v_bfe_u32 v157, v165, 16, 1
	v_add3_u32 v165, v165, v157, s97
	global_store_short_d16_hi v124, v164, s[12:13]
	s_add_u32 s12, s12, 0x1000
	s_addc_u32 s13, s13, 0
	global_store_short_d16_hi v124, v165, s[12:13]
	s_add_u32 s12, s12, 0x1000
	s_addc_u32 s13, s13, 0

.Lrw_go_2:
	ds_read2st64_b32 v[150:151], v146 offset0:16 offset1:20
	ds_read2st64_b32 v[152:153], v147 offset0:16 offset1:20
	ds_read2_b32 v[154:155], v148 offset0:16 offset1:20
	v_lshlrev_b32_e32 v132, 16, v132
	v_lshlrev_b32_e32 v133, 16, v133
	s_waitcnt lgkmcnt(0)
	v_pk_mov_b32 v[156:157], v[150:151], v[150:151] op_sel:[0,1]
	s_nop 1
	v_permlane32_swap_b32_e32 v156, v157
	v_add_f32_e32 v156, v156, v157
	v_pk_mul_f32 v[162:163], v[132:133], s[8:9] op_sel_hi:[1,0]
	v_exp_f32_e32 v162, v162
	v_add_f32_dpp v156, v156, v156 quad_perm:[1,0,3,2] row_mask:0xf bank_mask:0xf bound_ctrl:1
	v_exp_f32_e32 v163, v163
	s_nop 0
	v_add_f32_dpp v156, v156, v156 quad_perm:[2,3,0,1] row_mask:0xf bank_mask:0xf bound_ctrl:1
	s_nop 0
	s_nop 0
	v_add_f32_dpp v156, v156, v156 row_half_mirror row_mask:0xf bank_mask:0xf bound_ctrl:1
	s_nop 0
	s_nop 0
	v_add_f32_dpp v156, v156, v156 row_mirror row_mask:0xf bank_mask:0xf bound_ctrl:1
	s_nop 0
	s_nop 0
	v_add_f32_dpp v156, v156, v156 row_bcast:15 row_mask:0xa bank_mask:0xf
	s_nop 0
	v_readlane_b32 s4, v156, 31
	v_readlane_b32 s5, v156, 63
	s_nop 1
	v_pk_fma_f32 v[150:151], s[4:5], v[124:125], v[150:151] op_sel:[0,1,0] op_sel_hi:[1,1,1]
	v_pk_mul_f32 v[158:159], v[150:151], v[150:151]
	s_nop 1
	v_permlane32_swap_b32_e32 v158, v159
	v_add_f32_e32 v158, v158, v159
	v_pk_add_f32 v[162:163], v[162:163], 1.0 op_sel_hi:[1,0]
	v_rcp_f32_e32 v162, v162
	v_add_f32_dpp v158, v158, v158 quad_perm:[1,0,3,2] row_mask:0xf bank_mask:0xf bound_ctrl:1
	v_rcp_f32_e32 v163, v163
	s_nop 0
	v_add_f32_dpp v158, v158, v158 quad_perm:[2,3,0,1] row_mask:0xf bank_mask:0xf bound_ctrl:1
	s_nop 0
	s_nop 0
	v_add_f32_dpp v158, v158, v158 row_half_mirror row_mask:0xf bank_mask:0xf bound_ctrl:1
	s_nop 0
	s_nop 0
	v_add_f32_dpp v158, v158, v158 row_mirror row_mask:0xf bank_mask:0xf bound_ctrl:1
	s_nop 0
	s_nop 0
	v_add_f32_dpp v158, v158, v158 row_bcast:15 row_mask:0xa bank_mask:0xf
	s_nop 0
	v_readlane_b32 s6, v158, 31
	v_readlane_b32 s7, v158, 63
	s_nop 1
	v_pk_fma_f32 v[160:161], s[6:7], v[126:127], v[126:127] op_sel:[0,0,1] op_sel_hi:[1,0,1]
	v_rsq_f32_e32 v160, v160
	v_rsq_f32_e32 v161, v161
	s_nop 0
	v_pk_mul_f32 v[164:165], v[150:151], v[160:161]
	v_pk_fma_f32 v[164:165], v[144:145], v[164:165], v[144:145] op_sel:[0,0,1] op_sel_hi:[0,1,1]
	v_pk_fma_f32 v[164:165], v[154:155], v[152:153], v[164:165]
	v_pk_mul_f32 v[164:165], v[164:165], v[132:133]
	v_pk_mul_f32 v[164:165], v[162:163], v[164:165]
	v_bfe_u32 v156, v164, 16, 1
	v_add3_u32 v164, v164, v156, s97
	v_bfe_u32 v157, v165, 16, 1
	v_add3_u32 v165, v165, v157, s97
	global_store_short_d16_hi v124, v164, s[12:13]
	s_add_u32 s12, s12, 0x1000
	s_addc_u32 s13, s13, 0
	global_store_short_d16_hi v124, v165, s[12:13]
	s_add_u32 s12, s12, 0x1000
	s_addc_u32 s13, s13, 0

.Lrw_go_3:
	ds_read2st64_b32 v[150:151], v146 offset0:24 offset1:28
	ds_read2st64_b32 v[152:153], v147 offset0:24 offset1:28
	ds_read2_b32 v[154:155], v148 offset0:24 offset1:28
	v_lshlrev_b32_e32 v134, 16, v134
	v_lshlrev_b32_e32 v135, 16, v135
	s_waitcnt lgkmcnt(0)
	v_pk_mov_b32 v[156:157], v[150:151], v[150:151] op_sel:[0,1]
	s_nop 1
	v_permlane32_swap_b32_e32 v156, v157
	v_add_f32_e32 v156, v156, v157
	v_pk_mul_f32 v[162:163], v[134:135], s[8:9] op_sel_hi:[1,0]
	v_exp_f32_e32 v162, v162
	v_add_f32_dpp v156, v156, v156 quad_perm:[1,0,3,2] row_mask:0xf bank_mask:0xf bound_ctrl:1
	v_exp_f32_e32 v163, v163
	s_nop 0
	v_add_f32_dpp v156, v156, v156 quad_perm:[2,3,0,1] row_mask:0xf bank_mask:0xf bound_ctrl:1
	s_nop 0
	s_nop 0
	v_add_f32_dpp v156, v156, v156 row_half_mirror row_mask:0xf bank_mask:0xf bound_ctrl:1
	s_nop 0
	s_nop 0
	v_add_f32_dpp v156, v156, v156 row_mirror row_mask:0xf bank_mask:0xf bound_ctrl:1
	s_nop 0
	s_nop 0
	v_add_f32_dpp v156, v156, v156 row_bcast:15 row_mask:0xa bank_mask:0xf
	s_nop 0
	v_readlane_b32 s4, v156, 31
	v_readlane_b32 s5, v156, 63
	s_nop 1
	v_pk_fma_f32 v[150:151], s[4:5], v[124:125], v[150:151] op_sel:[0,1,0] op_sel_hi:[1,1,1]
	v_pk_mul_f32 v[158:159], v[150:151], v[150:151]
	s_nop 1
	v_permlane32_swap_b32_e32 v158, v159
	v_add_f32_e32 v158, v158, v159
	v_pk_add_f32 v[162:163], v[162:163], 1.0 op_sel_hi:[1,0]
	v_rcp_f32_e32 v162, v162
	v_add_f32_dpp v158, v158, v158 quad_perm:[1,0,3,2] row_mask:0xf bank_mask:0xf bound_ctrl:1
	v_rcp_f32_e32 v163, v163
	s_nop 0
	v_add_f32_dpp v158, v158, v158 quad_perm:[2,3,0,1] row_mask:0xf bank_mask:0xf bound_ctrl:1
	s_nop 0
	s_nop 0
	v_add_f32_dpp v158, v158, v158 row_half_mirror row_mask:0xf bank_mask:0xf bound_ctrl:1
	s_nop 0
	s_nop 0
	v_add_f32_dpp v158, v158, v158 row_mirror row_mask:0xf bank_mask:0xf bound_ctrl:1
	s_nop 0
	s_nop 0
	v_add_f32_dpp v158, v158, v158 row_bcast:15 row_mask:0xa bank_mask:0xf
	s_nop 0
	v_readlane_b32 s6, v158, 31
	v_readlane_b32 s7, v158, 63
	s_nop 1
	v_pk_fma_f32 v[160:161], s[6:7], v[126:127], v[126:127] op_sel:[0,0,1] op_sel_hi:[1,0,1]
	v_rsq_f32_e32 v160, v160
	v_rsq_f32_e32 v161, v161
	s_nop 0
	v_pk_mul_f32 v[164:165], v[150:151], v[160:161]
	v_pk_fma_f32 v[164:165], v[144:145], v[164:165], v[144:145] op_sel:[0,0,1] op_sel_hi:[0,1,1]
	v_pk_fma_f32 v[164:165], v[154:155], v[152:153], v[164:165]
	v_pk_mul_f32 v[164:165], v[164:165], v[134:135]
	v_pk_mul_f32 v[164:165], v[162:163], v[164:165]
	v_bfe_u32 v156, v164, 16, 1
	v_add3_u32 v164, v164, v156, s97
	v_bfe_u32 v157, v165, 16, 1
	v_add3_u32 v165, v165, v157, s97
	global_store_short_d16_hi v124, v164, s[12:13]
	s_add_u32 s12, s12, 0x1000
	s_addc_u32 s13, s13, 0
	global_store_short_d16_hi v124, v165, s[12:13]
	s_add_u32 s12, s12, 0x1000
	s_addc_u32 s13, s13, 0

.Lrw_go_4:
	ds_read2st64_b32 v[150:151], v146 offset0:32 offset1:36
	ds_read2st64_b32 v[152:153], v147 offset0:32 offset1:36
	ds_read2_b32 v[154:155], v148 offset0:32 offset1:36
	v_lshlrev_b32_e32 v136, 16, v136
	v_lshlrev_b32_e32 v137, 16, v137
	s_waitcnt lgkmcnt(0)
	v_pk_mov_b32 v[156:157], v[150:151], v[150:151] op_sel:[0,1]
	s_nop 1
	v_permlane32_swap_b32_e32 v156, v157
	v_add_f32_e32 v156, v156, v157
	v_pk_mul_f32 v[162:163], v[136:137], s[8:9] op_sel_hi:[1,0]
	v_exp_f32_e32 v162, v162
	v_add_f32_dpp v156, v156, v156 quad_perm:[1,0,3,2] row_mask:0xf bank_mask:0xf bound_ctrl:1
	v_exp_f32_e32 v163, v163
	s_nop 0
	v_add_f32_dpp v156, v156, v156 quad_perm:[2,3,0,1] row_mask:0xf bank_mask:0xf bound_ctrl:1
	s_nop 0
	s_nop 0
	v_add_f32_dpp v156, v156, v156 row_half_mirror row_mask:0xf bank_mask:0xf bound_ctrl:1
	s_nop 0
	s_nop 0
	v_add_f32_dpp v156, v156, v156 row_mirror row_mask:0xf bank_mask:0xf bound_ctrl:1
	s_nop 0
	s_nop 0
	v_add_f32_dpp v156, v156, v156 row_bcast:15 row_mask:0xa bank_mask:0xf
	s_nop 0
	v_readlane_b32 s4, v156, 31
	v_readlane_b32 s5, v156, 63
	s_nop 1
	v_pk_fma_f32 v[150:151], s[4:5], v[124:125], v[150:151] op_sel:[0,1,0] op_sel_hi:[1,1,1]
	v_pk_mul_f32 v[158:159], v[150:151], v[150:151]
	s_nop 1
	v_permlane32_swap_b32_e32 v158, v159
	v_add_f32_e32 v158, v158, v159
	v_pk_add_f32 v[162:163], v[162:163], 1.0 op_sel_hi:[1,0]
	v_rcp_f32_e32 v162, v162
	v_add_f32_dpp v158, v158, v158 quad_perm:[1,0,3,2] row_mask:0xf bank_mask:0xf bound_ctrl:1
	v_rcp_f32_e32 v163, v163
	s_nop 0
	v_add_f32_dpp v158, v158, v158 quad_perm:[2,3,0,1] row_mask:0xf bank_mask:0xf bound_ctrl:1
	s_nop 0
	s_nop 0
	v_add_f32_dpp v158, v158, v158 row_half_mirror row_mask:0xf bank_mask:0xf bound_ctrl:1
	s_nop 0
	s_nop 0
	v_add_f32_dpp v158, v158, v158 row_mirror row_mask:0xf bank_mask:0xf bound_ctrl:1
	s_nop 0
	s_nop 0
	v_add_f32_dpp v158, v158, v158 row_bcast:15 row_mask:0xa bank_mask:0xf
	s_nop 0
	v_readlane_b32 s6, v158, 31
	v_readlane_b32 s7, v158, 63
	s_nop 1
	v_pk_fma_f32 v[160:161], s[6:7], v[126:127], v[126:127] op_sel:[0,0,1] op_sel_hi:[1,0,1]
	v_rsq_f32_e32 v160, v160
	v_rsq_f32_e32 v161, v161
	s_nop 0
	v_pk_mul_f32 v[164:165], v[150:151], v[160:161]
	v_pk_fma_f32 v[164:165], v[144:145], v[164:165], v[144:145] op_sel:[0,0,1] op_sel_hi:[0,1,1]
	v_pk_fma_f32 v[164:165], v[154:155], v[152:153], v[164:165]
	v_pk_mul_f32 v[164:165], v[164:165], v[136:137]
	v_pk_mul_f32 v[164:165], v[162:163], v[164:165]
	v_bfe_u32 v156, v164, 16, 1
	v_add3_u32 v164, v164, v156, s97
	v_bfe_u32 v157, v165, 16, 1
	v_add3_u32 v165, v165, v157, s97
	global_store_short_d16_hi v124, v164, s[12:13]
	s_add_u32 s12, s12, 0x1000
	s_addc_u32 s13, s13, 0
	global_store_short_d16_hi v124, v165, s[12:13]
	s_add_u32 s12, s12, 0x1000
	s_addc_u32 s13, s13, 0

.Lrw_go_5:
	ds_read2st64_b32 v[150:151], v146 offset0:40 offset1:44
	ds_read2st64_b32 v[152:153], v147 offset0:40 offset1:44
	ds_read2_b32 v[154:155], v148 offset0:40 offset1:44
	v_lshlrev_b32_e32 v138, 16, v138
	v_lshlrev_b32_e32 v139, 16, v139
	s_waitcnt lgkmcnt(0)
	v_pk_mov_b32 v[156:157], v[150:151], v[150:151] op_sel:[0,1]
	s_nop 1
	v_permlane32_swap_b32_e32 v156, v157
	v_add_f32_e32 v156, v156, v157
	v_pk_mul_f32 v[162:163], v[138:139], s[8:9] op_sel_hi:[1,0]
	v_exp_f32_e32 v162, v162
	v_add_f32_dpp v156, v156, v156 quad_perm:[1,0,3,2] row_mask:0xf bank_mask:0xf bound_ctrl:1
	v_exp_f32_e32 v163, v163
	s_nop 0
	v_add_f32_dpp v156, v156, v156 quad_perm:[2,3,0,1] row_mask:0xf bank_mask:0xf bound_ctrl:1
	s_nop 0
	s_nop 0
	v_add_f32_dpp v156, v156, v156 row_half_mirror row_mask:0xf bank_mask:0xf bound_ctrl:1
	s_nop 0
	s_nop 0
	v_add_f32_dpp v156, v156, v156 row_mirror row_mask:0xf bank_mask:0xf bound_ctrl:1
	s_nop 0
	s_nop 0
	v_add_f32_dpp v156, v156, v156 row_bcast:15 row_mask:0xa bank_mask:0xf
	s_nop 0
	v_readlane_b32 s4, v156, 31
	v_readlane_b32 s5, v156, 63
	s_nop 1
	v_pk_fma_f32 v[150:151], s[4:5], v[124:125], v[150:151] op_sel:[0,1,0] op_sel_hi:[1,1,1]
	v_pk_mul_f32 v[158:159], v[150:151], v[150:151]
	s_nop 1
	v_permlane32_swap_b32_e32 v158, v159
	v_add_f32_e32 v158, v158, v159
	v_pk_add_f32 v[162:163], v[162:163], 1.0 op_sel_hi:[1,0]
	v_rcp_f32_e32 v162, v162
	v_add_f32_dpp v158, v158, v158 quad_perm:[1,0,3,2] row_mask:0xf bank_mask:0xf bound_ctrl:1
	v_rcp_f32_e32 v163, v163
	s_nop 0
	v_add_f32_dpp v158, v158, v158 quad_perm:[2,3,0,1] row_mask:0xf bank_mask:0xf bound_ctrl:1
	s_nop 0
	s_nop 0
	v_add_f32_dpp v158, v158, v158 row_half_mirror row_mask:0xf bank_mask:0xf bound_ctrl:1
	s_nop 0
	s_nop 0
	v_add_f32_dpp v158, v158, v158 row_mirror row_mask:0xf bank_mask:0xf bound_ctrl:1
	s_nop 0
	s_nop 0
	v_add_f32_dpp v158, v158, v158 row_bcast:15 row_mask:0xa bank_mask:0xf
	s_nop 0
	v_readlane_b32 s6, v158, 31
	v_readlane_b32 s7, v158, 63
	s_nop 1
	v_pk_fma_f32 v[160:161], s[6:7], v[126:127], v[126:127] op_sel:[0,0,1] op_sel_hi:[1,0,1]
	v_rsq_f32_e32 v160, v160
	v_rsq_f32_e32 v161, v161
	s_nop 0
	v_pk_mul_f32 v[164:165], v[150:151], v[160:161]
	v_pk_fma_f32 v[164:165], v[144:145], v[164:165], v[144:145] op_sel:[0,0,1] op_sel_hi:[0,1,1]
	v_pk_fma_f32 v[164:165], v[154:155], v[152:153], v[164:165]
	v_pk_mul_f32 v[164:165], v[164:165], v[138:139]
	v_pk_mul_f32 v[164:165], v[162:163], v[164:165]
	v_bfe_u32 v156, v164, 16, 1
	v_add3_u32 v164, v164, v156, s97
	v_bfe_u32 v157, v165, 16, 1
	v_add3_u32 v165, v165, v157, s97
	global_store_short_d16_hi v124, v164, s[12:13]
	s_add_u32 s12, s12, 0x1000
	s_addc_u32 s13, s13, 0
	global_store_short_d16_hi v124, v165, s[12:13]
	s_add_u32 s12, s12, 0x1000
	s_addc_u32 s13, s13, 0

.Lrw_go_6:
	ds_read2st64_b32 v[150:151], v146 offset0:48 offset1:52
	ds_read2st64_b32 v[152:153], v147 offset0:48 offset1:52
	ds_read2_b32 v[154:155], v148 offset0:48 offset1:52
	v_lshlrev_b32_e32 v140, 16, v140
	v_lshlrev_b32_e32 v141, 16, v141
	s_waitcnt lgkmcnt(0)
	v_pk_mov_b32 v[156:157], v[150:151], v[150:151] op_sel:[0,1]
	s_nop 1
	v_permlane32_swap_b32_e32 v156, v157
	v_add_f32_e32 v156, v156, v157
	v_pk_mul_f32 v[162:163], v[140:141], s[8:9] op_sel_hi:[1,0]
	v_exp_f32_e32 v162, v162
	v_add_f32_dpp v156, v156, v156 quad_perm:[1,0,3,2] row_mask:0xf bank_mask:0xf bound_ctrl:1
	v_exp_f32_e32 v163, v163
	s_nop 0
	v_add_f32_dpp v156, v156, v156 quad_perm:[2,3,0,1] row_mask:0xf bank_mask:0xf bound_ctrl:1
	s_nop 0
	s_nop 0
	v_add_f32_dpp v156, v156, v156 row_half_mirror row_mask:0xf bank_mask:0xf bound_ctrl:1
	s_nop 0
	s_nop 0
	v_add_f32_dpp v156, v156, v156 row_mirror row_mask:0xf bank_mask:0xf bound_ctrl:1
	s_nop 0
	s_nop 0
	v_add_f32_dpp v156, v156, v156 row_bcast:15 row_mask:0xa bank_mask:0xf
	s_nop 0
	v_readlane_b32 s4, v156, 31
	v_readlane_b32 s5, v156, 63
	s_nop 1
	v_pk_fma_f32 v[150:151], s[4:5], v[124:125], v[150:151] op_sel:[0,1,0] op_sel_hi:[1,1,1]
	v_pk_mul_f32 v[158:159], v[150:151], v[150:151]
	s_nop 1
	v_permlane32_swap_b32_e32 v158, v159
	v_add_f32_e32 v158, v158, v159
	v_pk_add_f32 v[162:163], v[162:163], 1.0 op_sel_hi:[1,0]
	v_rcp_f32_e32 v162, v162
	v_add_f32_dpp v158, v158, v158 quad_perm:[1,0,3,2] row_mask:0xf bank_mask:0xf bound_ctrl:1
	v_rcp_f32_e32 v163, v163
	s_nop 0
	v_add_f32_dpp v158, v158, v158 quad_perm:[2,3,0,1] row_mask:0xf bank_mask:0xf bound_ctrl:1
	s_nop 0
	s_nop 0
	v_add_f32_dpp v158, v158, v158 row_half_mirror row_mask:0xf bank_mask:0xf bound_ctrl:1
	s_nop 0
	s_nop 0
	v_add_f32_dpp v158, v158, v158 row_mirror row_mask:0xf bank_mask:0xf bound_ctrl:1
	s_nop 0
	s_nop 0
	v_add_f32_dpp v158, v158, v158 row_bcast:15 row_mask:0xa bank_mask:0xf
	s_nop 0
	v_readlane_b32 s6, v158, 31
	v_readlane_b32 s7, v158, 63
	s_nop 1
	v_pk_fma_f32 v[160:161], s[6:7], v[126:127], v[126:127] op_sel:[0,0,1] op_sel_hi:[1,0,1]
	v_rsq_f32_e32 v160, v160
	v_rsq_f32_e32 v161, v161
	s_nop 0
	v_pk_mul_f32 v[164:165], v[150:151], v[160:161]
	v_pk_fma_f32 v[164:165], v[144:145], v[164:165], v[144:145] op_sel:[0,0,1] op_sel_hi:[0,1,1]
	v_pk_fma_f32 v[164:165], v[154:155], v[152:153], v[164:165]
	v_pk_mul_f32 v[164:165], v[164:165], v[140:141]
	v_pk_mul_f32 v[164:165], v[162:163], v[164:165]
	v_bfe_u32 v156, v164, 16, 1
	v_add3_u32 v164, v164, v156, s97
	v_bfe_u32 v157, v165, 16, 1
	v_add3_u32 v165, v165, v157, s97
	global_store_short_d16_hi v124, v164, s[12:13]
	s_add_u32 s12, s12, 0x1000
	s_addc_u32 s13, s13, 0
	global_store_short_d16_hi v124, v165, s[12:13]
	s_add_u32 s12, s12, 0x1000
	s_addc_u32 s13, s13, 0

.Lrw_go_7:
	ds_read2st64_b32 v[150:151], v146 offset0:56 offset1:60
	ds_read2st64_b32 v[152:153], v147 offset0:56 offset1:60
	ds_read2_b32 v[154:155], v148 offset0:56 offset1:60
	v_lshlrev_b32_e32 v142, 16, v142
	v_lshlrev_b32_e32 v143, 16, v143
	s_waitcnt lgkmcnt(0)
	v_pk_mov_b32 v[156:157], v[150:151], v[150:151] op_sel:[0,1]
	s_nop 1
	v_permlane32_swap_b32_e32 v156, v157
	v_add_f32_e32 v156, v156, v157
	v_pk_mul_f32 v[162:163], v[142:143], s[8:9] op_sel_hi:[1,0]
	v_exp_f32_e32 v162, v162
	v_add_f32_dpp v156, v156, v156 quad_perm:[1,0,3,2] row_mask:0xf bank_mask:0xf bound_ctrl:1
	v_exp_f32_e32 v163, v163
	s_nop 0
	v_add_f32_dpp v156, v156, v156 quad_perm:[2,3,0,1] row_mask:0xf bank_mask:0xf bound_ctrl:1
	s_nop 0
	s_nop 0
	v_add_f32_dpp v156, v156, v156 row_half_mirror row_mask:0xf bank_mask:0xf bound_ctrl:1
	s_nop 0
	s_nop 0
	v_add_f32_dpp v156, v156, v156 row_mirror row_mask:0xf bank_mask:0xf bound_ctrl:1
	s_nop 0
	s_nop 0
	v_add_f32_dpp v156, v156, v156 row_bcast:15 row_mask:0xa bank_mask:0xf
	s_nop 0
	v_readlane_b32 s4, v156, 31
	v_readlane_b32 s5, v156, 63
	s_nop 1
	v_pk_fma_f32 v[150:151], s[4:5], v[124:125], v[150:151] op_sel:[0,1,0] op_sel_hi:[1,1,1]
	v_pk_mul_f32 v[158:159], v[150:151], v[150:151]
	s_nop 1
	v_permlane32_swap_b32_e32 v158, v159
	v_add_f32_e32 v158, v158, v159
	v_pk_add_f32 v[162:163], v[162:163], 1.0 op_sel_hi:[1,0]
	v_rcp_f32_e32 v162, v162
	v_add_f32_dpp v158, v158, v158 quad_perm:[1,0,3,2] row_mask:0xf bank_mask:0xf bound_ctrl:1
	v_rcp_f32_e32 v163, v163
	s_nop 0
	v_add_f32_dpp v158, v158, v158 quad_perm:[2,3,0,1] row_mask:0xf bank_mask:0xf bound_ctrl:1
	s_nop 0
	s_nop 0
	v_add_f32_dpp v158, v158, v158 row_half_mirror row_mask:0xf bank_mask:0xf bound_ctrl:1
	s_nop 0
	s_nop 0
	v_add_f32_dpp v158, v158, v158 row_mirror row_mask:0xf bank_mask:0xf bound_ctrl:1
	s_nop 0
	s_nop 0
	v_add_f32_dpp v158, v158, v158 row_bcast:15 row_mask:0xa bank_mask:0xf
	s_nop 0
	v_readlane_b32 s6, v158, 31
	v_readlane_b32 s7, v158, 63
	s_nop 1
	v_pk_fma_f32 v[160:161], s[6:7], v[126:127], v[126:127] op_sel:[0,0,1] op_sel_hi:[1,0,1]
	v_rsq_f32_e32 v160, v160
	v_rsq_f32_e32 v161, v161
	s_nop 0
	v_pk_mul_f32 v[164:165], v[150:151], v[160:161]
	v_pk_fma_f32 v[164:165], v[144:145], v[164:165], v[144:145] op_sel:[0,0,1] op_sel_hi:[0,1,1]
	v_pk_fma_f32 v[164:165], v[154:155], v[152:153], v[164:165]
	v_pk_mul_f32 v[164:165], v[164:165], v[142:143]
	v_pk_mul_f32 v[164:165], v[162:163], v[164:165]
	v_bfe_u32 v156, v164, 16, 1
	v_add3_u32 v164, v164, v156, s97
	v_bfe_u32 v157, v165, 16, 1
	v_add3_u32 v165, v165, v157, s97
	global_store_short_d16_hi v124, v164, s[12:13]
	s_add_u32 s12, s12, 0x1000
	s_addc_u32 s13, s13, 0
	global_store_short_d16_hi v124, v165, s[12:13]
	s_add_u32 s12, s12, 0x1000
	s_addc_u32 s13, s13, 0
	s_cmp_lg_u32 s40, 31
	s_cbranch_scc0 .Lrw_noladder
	s_waitcnt vmcnt(14)
	v_lshlrev_b32_e32 v106, 16, v52
	v_lshlrev_b32_e32 v35, 16, v53
	v_lshlrev_b32_e32 v34, 16, v54
	v_lshlrev_b32_e32 v44, 16, v18
	v_lshlrev_b32_e32 v1, 16, v1
	v_lshlrev_b32_e32 v46, 16, v19
	v_lshlrev_b32_e32 v48, 16, v20
	v_lshlrev_b32_e32 v45, 16, v21
	v_lshlrev_b32_e32 v47, 16, v22
	v_lshlrev_b32_e32 v51, 16, v23
	v_lshlrev_b32_e32 v54, 16, v24
	v_lshlrev_b32_e32 v52, 16, v25
	v_lshlrev_b32_e32 v50, 16, v27
	v_lshlrev_b32_e32 v49, 16, v28
	v_lshlrev_b32_e32 v53, 16, v29
	v_lshlrev_b32_e32 v57, 16, v31
	v_lshlrev_b32_e32 v60, 16, v32
	v_lshlrev_b32_e32 v58, 16, v33
	v_lshlrev_b32_e32 v56, 16, v55
	v_lshlrev_b32_e32 v55, 16, v30
	v_lshlrev_b32_e32 v59, 16, v59
	v_lshlrev_b32_e32 v61, 16, v61
	v_lshlrev_b32_e32 v62, 16, v62
	v_lshlrev_b32_e32 v63, 16, v63
	v_lshlrev_b32_e32 v66, 16, v66
	v_lshlrev_b32_e32 v64, 16, v64
	v_lshlrev_b32_e32 v65, 16, v6
	v_lshlrev_b32_e32 v67, 16, v7
	v_lshlrev_b32_e32 v70, 16, v12
	v_lshlrev_b32_e32 v72, 16, v13
	v_lshlrev_b32_e32 v68, 16, v16
	v_lshlrev_b32_e32 v69, 16, v17
	v_lshlrev_b32_e32 v71, 16, v8
	v_lshlrev_b32_e32 v74, 16, v9
	v_lshlrev_b32_e32 v73, 16, v4
	s_branch .Lrw_noladder
